# v15 plus prep phase adaLN staging: 33 silu(c) loads issued together with counted vmcnt instead of one load per loop trip
# speedup vs baseline: 1.0011x; 1.0001x over previous
; DI float silu_f(float x) { return x * __builtin_amdgcn_rcpf(1.f + __expf(-x)); }
; DI void prep_mod_item(const Params& p, int item, float* smem) {
;     ...
;     __syncthreads();
;     for (int e = tid; e < 33 * 512; e += NTHR) {
;       const int kk = e & 511, b = e >> 9;
;       const int k = half * 512 + kk;
;       const float v = (b < 32) ? p.c[b * 1024 + k] : p.c_ctx[k];
;       smem[e] = silu_f(v);
;     }
;     __syncthreads();
.LBB0_63:
	s_waitcnt lgkmcnt(0)
	s_barrier
	s_and_saveexec_b64 s[0:1], s[6:7]
	s_cbranch_execz .LBB0_66
	v_or_b32_e32 v0, s2, v193
	v_lshlrev_b32_e32 v2, 2, v0
	s_mov_b64 s[100:101], s[54:55]
	global_load_dword v225, v2, s[100:101]
	s_add_u32 s100, s100, 0x1000
	s_addc_u32 s101, s101, 0
	global_load_dword v226, v2, s[100:101]
	s_add_u32 s100, s100, 0x1000
	s_addc_u32 s101, s101, 0
	global_load_dword v227, v2, s[100:101]
	s_add_u32 s100, s100, 0x1000
	s_addc_u32 s101, s101, 0
	global_load_dword v228, v2, s[100:101]
	s_add_u32 s100, s100, 0x1000
	s_addc_u32 s101, s101, 0
	global_load_dword v229, v2, s[100:101]
	s_add_u32 s100, s100, 0x1000
	s_addc_u32 s101, s101, 0
	global_load_dword v230, v2, s[100:101]
	s_add_u32 s100, s100, 0x1000
	s_addc_u32 s101, s101, 0
	global_load_dword v231, v2, s[100:101]
	s_add_u32 s100, s100, 0x1000
	s_addc_u32 s101, s101, 0
	global_load_dword v232, v2, s[100:101]
	s_add_u32 s100, s100, 0x1000
	s_addc_u32 s101, s101, 0
	global_load_dword v233, v2, s[100:101]
	s_add_u32 s100, s100, 0x1000
	s_addc_u32 s101, s101, 0
	global_load_dword v234, v2, s[100:101]
	s_add_u32 s100, s100, 0x1000
	s_addc_u32 s101, s101, 0
	global_load_dword v235, v2, s[100:101]
	s_add_u32 s100, s100, 0x1000
	s_addc_u32 s101, s101, 0
	global_load_dword v236, v2, s[100:101]
	s_add_u32 s100, s100, 0x1000
	s_addc_u32 s101, s101, 0
	global_load_dword v237, v2, s[100:101]
	s_add_u32 s100, s100, 0x1000
	s_addc_u32 s101, s101, 0
	global_load_dword v238, v2, s[100:101]
	s_add_u32 s100, s100, 0x1000
	s_addc_u32 s101, s101, 0
	global_load_dword v239, v2, s[100:101]
	s_add_u32 s100, s100, 0x1000
	s_addc_u32 s101, s101, 0
	global_load_dword v240, v2, s[100:101]
	s_add_u32 s100, s100, 0x1000
	s_addc_u32 s101, s101, 0
	global_load_dword v241, v2, s[100:101]
	s_add_u32 s100, s100, 0x1000
	s_addc_u32 s101, s101, 0
	global_load_dword v242, v2, s[100:101]
	s_add_u32 s100, s100, 0x1000
	s_addc_u32 s101, s101, 0
	global_load_dword v243, v2, s[100:101]
	s_add_u32 s100, s100, 0x1000
	s_addc_u32 s101, s101, 0
	global_load_dword v244, v2, s[100:101]
	s_add_u32 s100, s100, 0x1000
	s_addc_u32 s101, s101, 0
	global_load_dword v245, v2, s[100:101]
	s_add_u32 s100, s100, 0x1000
	s_addc_u32 s101, s101, 0
	global_load_dword v246, v2, s[100:101]
	s_add_u32 s100, s100, 0x1000
	s_addc_u32 s101, s101, 0
	global_load_dword v247, v2, s[100:101]
	s_add_u32 s100, s100, 0x1000
	s_addc_u32 s101, s101, 0
	global_load_dword v248, v2, s[100:101]
	s_add_u32 s100, s100, 0x1000
	s_addc_u32 s101, s101, 0
	global_load_dword v249, v2, s[100:101]
	s_add_u32 s100, s100, 0x1000
	s_addc_u32 s101, s101, 0
	global_load_dword v250, v2, s[100:101]
	s_add_u32 s100, s100, 0x1000
	s_addc_u32 s101, s101, 0
	global_load_dword v251, v2, s[100:101]
	s_add_u32 s100, s100, 0x1000
	s_addc_u32 s101, s101, 0
	global_load_dword v252, v2, s[100:101]
	s_add_u32 s100, s100, 0x1000
	s_addc_u32 s101, s101, 0
	global_load_dword v253, v2, s[100:101]
	s_add_u32 s100, s100, 0x1000
	s_addc_u32 s101, s101, 0
	global_load_dword v200, v2, s[100:101]
	s_add_u32 s100, s100, 0x1000
	s_addc_u32 s101, s101, 0
	global_load_dword v201, v2, s[100:101]
	s_add_u32 s100, s100, 0x1000
	s_addc_u32 s101, s101, 0
	global_load_dword v202, v2, s[100:101]
	global_load_dword v203, v2, s[58:59]
	v_add_u32_e32 v4, 0x10000, v194
	s_waitcnt vmcnt(32)
	v_mul_f32_e32 v8, 0xbfb8aa3b, v225
	v_exp_f32_e32 v8, v8
	s_nop 0
	v_add_f32_e32 v5, 1.0, v8
	v_rcp_f32_e32 v8, v5
	s_nop 0
	v_mul_f32_e32 v6, v225, v8
	ds_write_b32 v194, v6
	s_waitcnt vmcnt(31)
	v_mul_f32_e32 v8, 0xbfb8aa3b, v226
	v_exp_f32_e32 v8, v8
	s_nop 0
	v_add_f32_e32 v5, 1.0, v8
	v_rcp_f32_e32 v8, v5
	s_nop 0
	v_mul_f32_e32 v6, v226, v8
	ds_write_b32 v194, v6 offset:2048
	s_waitcnt vmcnt(30)
	v_mul_f32_e32 v8, 0xbfb8aa3b, v227
	v_exp_f32_e32 v8, v8
	s_nop 0
	v_add_f32_e32 v5, 1.0, v8
	v_rcp_f32_e32 v8, v5
	s_nop 0
	v_mul_f32_e32 v6, v227, v8
	ds_write_b32 v194, v6 offset:4096
	s_waitcnt vmcnt(29)
	v_mul_f32_e32 v8, 0xbfb8aa3b, v228
	v_exp_f32_e32 v8, v8
	s_nop 0
	v_add_f32_e32 v5, 1.0, v8
	v_rcp_f32_e32 v8, v5
	s_nop 0
	v_mul_f32_e32 v6, v228, v8
	ds_write_b32 v194, v6 offset:6144
	s_waitcnt vmcnt(28)
	v_mul_f32_e32 v8, 0xbfb8aa3b, v229
	v_exp_f32_e32 v8, v8
	s_nop 0
	v_add_f32_e32 v5, 1.0, v8
	v_rcp_f32_e32 v8, v5
	s_nop 0
	v_mul_f32_e32 v6, v229, v8
	ds_write_b32 v194, v6 offset:8192
	s_waitcnt vmcnt(27)
	v_mul_f32_e32 v8, 0xbfb8aa3b, v230
	v_exp_f32_e32 v8, v8
	s_nop 0
	v_add_f32_e32 v5, 1.0, v8
	v_rcp_f32_e32 v8, v5
	s_nop 0
	v_mul_f32_e32 v6, v230, v8
	ds_write_b32 v194, v6 offset:10240
	s_waitcnt vmcnt(26)
	v_mul_f32_e32 v8, 0xbfb8aa3b, v231
	v_exp_f32_e32 v8, v8
	s_nop 0
	v_add_f32_e32 v5, 1.0, v8
	v_rcp_f32_e32 v8, v5
	s_nop 0
	v_mul_f32_e32 v6, v231, v8
	ds_write_b32 v194, v6 offset:12288
	s_waitcnt vmcnt(25)
	v_mul_f32_e32 v8, 0xbfb8aa3b, v232
	v_exp_f32_e32 v8, v8
	s_nop 0
	v_add_f32_e32 v5, 1.0, v8
	v_rcp_f32_e32 v8, v5
	s_nop 0
	v_mul_f32_e32 v6, v232, v8
	ds_write_b32 v194, v6 offset:14336
	s_waitcnt vmcnt(24)
	v_mul_f32_e32 v8, 0xbfb8aa3b, v233
	v_exp_f32_e32 v8, v8
	s_nop 0
	v_add_f32_e32 v5, 1.0, v8
	v_rcp_f32_e32 v8, v5
	s_nop 0
	v_mul_f32_e32 v6, v233, v8
	ds_write_b32 v194, v6 offset:16384
	s_waitcnt vmcnt(23)
; DI float silu_f(float x) { return x * __builtin_amdgcn_rcpf(1.f + __expf(-x)); }
; DI void prep_mod_item(const Params& p, int item, float* smem) {
;     ...
;     for (int e = tid; e < 33 * 512; e += NTHR) {
;       const int kk = e & 511, b = e >> 9;
;       const int k = half * 512 + kk;
;       const float v = (b < 32) ? p.c[b * 1024 + k] : p.c_ctx[k];
;       smem[e] = silu_f(v);
;     }
;     __syncthreads();
	v_mul_f32_e32 v8, 0xbfb8aa3b, v234
	v_exp_f32_e32 v8, v8
	s_nop 0
	v_add_f32_e32 v5, 1.0, v8
	v_rcp_f32_e32 v8, v5
	s_nop 0
	v_mul_f32_e32 v6, v234, v8
	ds_write_b32 v194, v6 offset:18432
	s_waitcnt vmcnt(22)
	v_mul_f32_e32 v8, 0xbfb8aa3b, v235
	v_exp_f32_e32 v8, v8
	s_nop 0
	v_add_f32_e32 v5, 1.0, v8
	v_rcp_f32_e32 v8, v5
	s_nop 0
	v_mul_f32_e32 v6, v235, v8
	ds_write_b32 v194, v6 offset:20480
	s_waitcnt vmcnt(21)
	v_mul_f32_e32 v8, 0xbfb8aa3b, v236
	v_exp_f32_e32 v8, v8
	s_nop 0
	v_add_f32_e32 v5, 1.0, v8
	v_rcp_f32_e32 v8, v5
	s_nop 0
	v_mul_f32_e32 v6, v236, v8
	ds_write_b32 v194, v6 offset:22528
	s_waitcnt vmcnt(20)
	v_mul_f32_e32 v8, 0xbfb8aa3b, v237
	v_exp_f32_e32 v8, v8
	s_nop 0
	v_add_f32_e32 v5, 1.0, v8
	v_rcp_f32_e32 v8, v5
	s_nop 0
	v_mul_f32_e32 v6, v237, v8
	ds_write_b32 v194, v6 offset:24576
	s_waitcnt vmcnt(19)
	v_mul_f32_e32 v8, 0xbfb8aa3b, v238
	v_exp_f32_e32 v8, v8
	s_nop 0
	v_add_f32_e32 v5, 1.0, v8
	v_rcp_f32_e32 v8, v5
	s_nop 0
	v_mul_f32_e32 v6, v238, v8
	ds_write_b32 v194, v6 offset:26624
	s_waitcnt vmcnt(18)
	v_mul_f32_e32 v8, 0xbfb8aa3b, v239
	v_exp_f32_e32 v8, v8
	s_nop 0
	v_add_f32_e32 v5, 1.0, v8
	v_rcp_f32_e32 v8, v5
	s_nop 0
	v_mul_f32_e32 v6, v239, v8
	ds_write_b32 v194, v6 offset:28672
	s_waitcnt vmcnt(17)
	v_mul_f32_e32 v8, 0xbfb8aa3b, v240
	v_exp_f32_e32 v8, v8
	s_nop 0
	v_add_f32_e32 v5, 1.0, v8
	v_rcp_f32_e32 v8, v5
	s_nop 0
	v_mul_f32_e32 v6, v240, v8
	ds_write_b32 v194, v6 offset:30720
	s_waitcnt vmcnt(16)
	v_mul_f32_e32 v8, 0xbfb8aa3b, v241
	v_exp_f32_e32 v8, v8
	s_nop 0
	v_add_f32_e32 v5, 1.0, v8
	v_rcp_f32_e32 v8, v5
	s_nop 0
	v_mul_f32_e32 v6, v241, v8
	ds_write_b32 v194, v6 offset:32768
	s_waitcnt vmcnt(15)
	v_mul_f32_e32 v8, 0xbfb8aa3b, v242
	v_exp_f32_e32 v8, v8
	s_nop 0
	v_add_f32_e32 v5, 1.0, v8
	v_rcp_f32_e32 v8, v5
	s_nop 0
	v_mul_f32_e32 v6, v242, v8
	ds_write_b32 v194, v6 offset:34816
	s_waitcnt vmcnt(14)
	v_mul_f32_e32 v8, 0xbfb8aa3b, v243
	v_exp_f32_e32 v8, v8
	s_nop 0
	v_add_f32_e32 v5, 1.0, v8
	v_rcp_f32_e32 v8, v5
	s_nop 0
	v_mul_f32_e32 v6, v243, v8
	ds_write_b32 v194, v6 offset:36864
	s_waitcnt vmcnt(13)
	v_mul_f32_e32 v8, 0xbfb8aa3b, v244
	v_exp_f32_e32 v8, v8
	s_nop 0
	v_add_f32_e32 v5, 1.0, v8
	v_rcp_f32_e32 v8, v5
	s_nop 0
	v_mul_f32_e32 v6, v244, v8
	ds_write_b32 v194, v6 offset:38912
	s_waitcnt vmcnt(12)
	v_mul_f32_e32 v8, 0xbfb8aa3b, v245
	v_exp_f32_e32 v8, v8
	s_nop 0
	v_add_f32_e32 v5, 1.0, v8
	v_rcp_f32_e32 v8, v5
	s_nop 0
	v_mul_f32_e32 v6, v245, v8
	ds_write_b32 v194, v6 offset:40960
	s_waitcnt vmcnt(11)
	v_mul_f32_e32 v8, 0xbfb8aa3b, v246
	v_exp_f32_e32 v8, v8
	s_nop 0
	v_add_f32_e32 v5, 1.0, v8
	v_rcp_f32_e32 v8, v5
	s_nop 0
	v_mul_f32_e32 v6, v246, v8
	ds_write_b32 v194, v6 offset:43008
	s_waitcnt vmcnt(10)
	v_mul_f32_e32 v8, 0xbfb8aa3b, v247
	v_exp_f32_e32 v8, v8
	s_nop 0
	v_add_f32_e32 v5, 1.0, v8
	v_rcp_f32_e32 v8, v5
	s_nop 0
	v_mul_f32_e32 v6, v247, v8
	ds_write_b32 v194, v6 offset:45056
	s_waitcnt vmcnt(9)
	v_mul_f32_e32 v8, 0xbfb8aa3b, v248
	v_exp_f32_e32 v8, v8
	s_nop 0
	v_add_f32_e32 v5, 1.0, v8
	v_rcp_f32_e32 v8, v5
	s_nop 0
	v_mul_f32_e32 v6, v248, v8
	ds_write_b32 v194, v6 offset:47104
	s_waitcnt vmcnt(8)
	v_mul_f32_e32 v8, 0xbfb8aa3b, v249
	v_exp_f32_e32 v8, v8
	s_nop 0
	v_add_f32_e32 v5, 1.0, v8
	v_rcp_f32_e32 v8, v5
	s_nop 0
	v_mul_f32_e32 v6, v249, v8
	ds_write_b32 v194, v6 offset:49152
	s_waitcnt vmcnt(7)
	v_mul_f32_e32 v8, 0xbfb8aa3b, v250
	v_exp_f32_e32 v8, v8
	s_nop 0
	v_add_f32_e32 v5, 1.0, v8
	v_rcp_f32_e32 v8, v5
	s_nop 0
	v_mul_f32_e32 v6, v250, v8
	ds_write_b32 v194, v6 offset:51200
	s_waitcnt vmcnt(6)
	v_mul_f32_e32 v8, 0xbfb8aa3b, v251
	v_exp_f32_e32 v8, v8
	s_nop 0
	v_add_f32_e32 v5, 1.0, v8
	v_rcp_f32_e32 v8, v5
	s_nop 0
	v_mul_f32_e32 v6, v251, v8
	ds_write_b32 v194, v6 offset:53248
	s_waitcnt vmcnt(5)
	v_mul_f32_e32 v8, 0xbfb8aa3b, v252
	v_exp_f32_e32 v8, v8
	s_nop 0
	v_add_f32_e32 v5, 1.0, v8
	v_rcp_f32_e32 v8, v5
	s_nop 0
	v_mul_f32_e32 v6, v252, v8
	ds_write_b32 v194, v6 offset:55296
	s_waitcnt vmcnt(4)
	v_mul_f32_e32 v8, 0xbfb8aa3b, v253
	v_exp_f32_e32 v8, v8
	s_nop 0
	v_add_f32_e32 v5, 1.0, v8
	v_rcp_f32_e32 v8, v5
	s_nop 0
	v_mul_f32_e32 v6, v253, v8
	ds_write_b32 v194, v6 offset:57344
	s_waitcnt vmcnt(3)
	v_mul_f32_e32 v8, 0xbfb8aa3b, v200
	v_exp_f32_e32 v8, v8
	s_nop 0
	v_add_f32_e32 v5, 1.0, v8
	v_rcp_f32_e32 v8, v5
	s_nop 0
	v_mul_f32_e32 v6, v200, v8
	ds_write_b32 v194, v6 offset:59392
	s_waitcnt vmcnt(2)
	v_mul_f32_e32 v8, 0xbfb8aa3b, v201
	v_exp_f32_e32 v8, v8
	s_nop 0
	v_add_f32_e32 v5, 1.0, v8
	v_rcp_f32_e32 v8, v5
	s_nop 0
	v_mul_f32_e32 v6, v201, v8
	ds_write_b32 v194, v6 offset:61440
	s_waitcnt vmcnt(1)
	v_mul_f32_e32 v8, 0xbfb8aa3b, v202
	v_exp_f32_e32 v8, v8
	s_nop 0
	v_add_f32_e32 v5, 1.0, v8
	v_rcp_f32_e32 v8, v5
	s_nop 0
	v_mul_f32_e32 v6, v202, v8
	ds_write_b32 v194, v6 offset:63488
	s_waitcnt vmcnt(0)
	v_mul_f32_e32 v8, 0xbfb8aa3b, v203
	v_exp_f32_e32 v8, v8
	s_nop 0
	v_add_f32_e32 v5, 1.0, v8
	v_rcp_f32_e32 v8, v5
	s_nop 0
	v_mul_f32_e32 v6, v203, v8
	ds_write_b32 v4, v6
	s_mov_b64 s[10:11], exec
